# add: loop-invariant gate weights / mlstm biases hoisted out of the prep item loops
# speedup vs baseline: 1.0310x; 1.0106x over previous
; DI float logsig(float x) { return fminf(x, 0.f) - __logf(1.f + __expf(-fabsf(x))); }
; DI int rot(int bx, int k, int G) { int r = bx + k; while (r >= G) r -= G; return r; }
; DI void mlstm_prep_item(const KP& P, int layer, int b, int tb, LAS unsigned char* lds) {
;     ...
;       Il[gi * 64 + t] = Gt[t * 16 + gi] + P.b_mlstm_i[layer * 8 + gi]; Fl[gi * 64 + t] = logsig(Gt[t * 16 + 8 + gi] + P.b_mlstm_f[layer * 8 + gi]); }
; DI void prep_phase(const KP& P, int layer, LAS unsigned char* lds) {
;     const int G = gridDim.x; constexpr int NBT = NB * NTB;
;     for (int it = blockIdx.x; it < NBT; it += G) mlstm_prep_item(P, layer, it / NTB, it % NTB, lds);
.LBB0_262:
	s_or_b64 exec, exec, s[0:1]
	v_readlane_b32 s0, v253, 27
	v_readlane_b32 s1, v253, 28
	s_and_b64 vcc, exec, s[0:1]
	v_readlane_b32 s4, v254, 27
	v_readlane_b32 s0, v251, 3
	s_waitcnt lgkmcnt(0)
	s_barrier
	s_cbranch_vccz .LBB0_278
	v_readlane_b32 s0, v254, 53
	s_lshl_b32 s6, s0, 3
	v_readlane_b32 s7, v251, 0
	v_readlane_b32 s1, v254, 54
	v_mbcnt_lo_u32_b32 v160, -1, 0
	v_mbcnt_hi_u32_b32 v160, -1, v160
	v_readlane_b32 s74, v251, 44
	v_readlane_b32 s75, v251, 45
	v_readlane_b32 s76, v251, 46
	v_readlane_b32 s77, v251, 47
	v_and_b32_e32 v160, 7, v160
	v_or_b32_e32 v160, s6, v160
	v_lshlrev_b32_e32 v160, 2, v160
	s_nop 2
	global_load_dword v161, v160, s[74:75]
	global_load_dword v162, v160, s[76:77]
	s_branch .LBB0_265

; DI float logsig(float x) { return fminf(x, 0.f) - __logf(1.f + __expf(-fabsf(x))); }
; DI void mlstm_prep_item(const KP& P, int layer, int b, int tb, LAS unsigned char* lds) {
;     ...
;     { const int t = tid >> 3, gi = tid & 7;
;       Il[gi * 64 + t] = Gt[t * 16 + gi] + P.b_mlstm_i[layer * 8 + gi]; Fl[gi * 64 + t] = logsig(Gt[t * 16 + 8 + gi] + P.b_mlstm_f[layer * 8 + gi]); }
;     __syncthreads();
;     if (tid < 8) { const int dir = tid >> 2;
;         float* FG = (float*)(P.ws + WS_FG); float* IG = (float*)(P.ws + WS_IG);
;         float run = 0.f;
;         for (int step = 0; step < 64; ++step) { const int t = dir ? 63 - step : step;
;             run += Fl[tid * 64 + t]; Fl[tid * 64 + t] = run; FG[(R0 + t) * 8 + tid] = run; IG[(R0 + t) * 8 + tid] = Il[tid * 64 + t] - run; } }
.LBB0_269:
	s_or_b64 exec, exec, s[4:5]
	v_and_b32_e32 v4, 7, v44
	v_or_b32_e32 v112, s6, v4
	v_readlane_b32 s12, v251, 42
	v_lshlrev_b64 v[0:1], 2, v[112:113]
	v_readlane_b32 s14, v251, 44
	v_readlane_b32 s15, v251, 45
	s_waitcnt lgkmcnt(0)
	s_barrier
	v_lshl_add_u64 v[2:3], s[14:15], 0, v[0:1]
	v_mov_b32_e32 v2, v161
	v_readlane_b32 s16, v251, 46
	v_readlane_b32 s17, v251, 47
	s_add_i32 s0, 0, 0x12000
	v_lshlrev_b32_e32 v5, 2, v4
	v_lshl_add_u64 v[0:1], s[16:17], 0, v[0:1]
	v_mov_b32_e32 v0, v162
	v_ashrrev_i32_e32 v1, 3, v76
	v_lshlrev_b32_e32 v3, 6, v1
	v_add3_u32 v3, s0, v3, v5
	ds_read_b32 v5, v3
	v_lshl_add_u32 v1, v4, 6, v1
	v_lshl_add_u32 v1, v1, 2, 0
	v_add_u32_e32 v4, 0x11800, v1
	s_mov_b32 s0, 0xbfb8aa3b
	v_add_u32_e32 v1, 0x11000, v1
	v_readlane_b32 s13, v251, 43
	v_readlane_b32 s18, v251, 48
	v_readlane_b32 s19, v251, 49
	v_readlane_b32 s20, v251, 50
	v_readlane_b32 s21, v251, 51
	v_readlane_b32 s22, v251, 52
	v_readlane_b32 s23, v251, 53
	v_readlane_b32 s24, v251, 54
	v_readlane_b32 s25, v251, 55
	v_readlane_b32 s26, v251, 56
	v_readlane_b32 s27, v251, 57
	s_waitcnt lgkmcnt(0)
	v_add_f32_e32 v2, v5, v2
	ds_write_b32 v4, v2
	ds_read_b32 v2, v3 offset:32
	s_waitcnt lgkmcnt(0)
	v_add_f32_e32 v0, v2, v0
	v_mul_f32_e64 v2, |v0|, s0
	v_exp_f32_e32 v2, v2
	s_mov_b32 s0, 0x800000
	v_min_f32_e32 v0, 0, v0
	v_add_f32_e32 v2, 1.0, v2
	v_cmp_gt_f32_e32 vcc, s0, v2
	s_mov_b32 s0, 0x3f317217
	s_nop 0
	v_cndmask_b32_e64 v3, 0, 32, vcc
	v_ldexp_f32 v2, v2, v3
	v_log_f32_e32 v2, v2
	v_cndmask_b32_e32 v3, 0, v148, vcc
	v_mul_f32_e32 v4, 0x3f317217, v2
	v_fma_f32 v4, v2, s0, -v4
	v_fmac_f32_e32 v4, 0x3377d1cf, v2
	s_mov_b32 s0, 0x7f800000
	v_fmac_f32_e32 v4, 0x3f317217, v2
	v_cmp_lt_f32_e64 vcc, |v2|, s0
	s_nop 1
	v_cndmask_b32_e32 v2, v2, v4, vcc
	v_sub_f32_e32 v2, v2, v3
	v_sub_f32_e32 v0, v0, v2
	v_cmp_gt_i32_e32 vcc, 8, v76
	ds_write_b32 v1, v0
	s_waitcnt lgkmcnt(0)
	s_barrier
	s_and_saveexec_b64 s[0:1], vcc
	v_readlane_b32 s14, v253, 29
	v_readlane_b32 s16, v253, 31
	v_readlane_b32 s15, v253, 30
	v_readlane_b32 s17, v253, 32
	s_cbranch_execz .LBB0_272
	v_cmp_gt_u32_e32 vcc, 4, v76
	v_lshlrev_b32_e32 v0, 8, v76
	v_ashrrev_i32_e32 v77, 31, v76
	v_mov_b32_e32 v6, 0
	v_mov_b32_e32 v7, 4
	v_mov_b32_e32 v17, 32
	s_mov_b32 s4, 0x11000
	v_mov_b32_e32 v5, 0xfc
	v_cndmask_b32_e32 v5, v5, v6, vcc
	v_cndmask_b32_e32 v8, -4, v7, vcc
	v_mov_b32_e32 v16, 0xffffffe0
	v_cndmask_b32_e32 v16, v16, v17, vcc
	v_add3_u32 v9, v0, v5, s4
	v_lshrrev_b32_e32 v10, 2, v5
	v_mov_b32_e32 v11, 0
	v_ashrrev_i32_e32 v17, 31, v16
	v_mov_b32_e32 v18, v9
	v_lshl_add_u64 v[10:11], s[2:3], 0, v[10:11]
	v_lshl_add_u64 v[10:11], v[10:11], 3, v[76:77]
	v_lshlrev_b64 v[10:11], 2, v[10:11]
	v_lshl_add_u64 v[12:13], s[14:15], 0, v[10:11]
	v_lshl_add_u64 v[14:15], s[16:17], 0, v[10:11]
	v_mov_b32_e32 v1, 0
	ds_read_b32 v20, v9
	ds_read_b32 v45, v9 offset:2048
	v_add_u32_e32 v9, v8, v9
	ds_read_b32 v21, v9
	ds_read_b32 v46, v9 offset:2048
	v_add_u32_e32 v9, v8, v9
	ds_read_b32 v22, v9
	ds_read_b32 v47, v9 offset:2048
	v_add_u32_e32 v9, v8, v9
	ds_read_b32 v23, v9
	ds_read_b32 v48, v9 offset:2048
	v_add_u32_e32 v9, v8, v9
	ds_read_b32 v24, v9
	ds_read_b32 v49, v9 offset:2048
	v_add_u32_e32 v9, v8, v9
	ds_read_b32 v25, v9
	ds_read_b32 v50, v9 offset:2048
	v_add_u32_e32 v9, v8, v9
	ds_read_b32 v26, v9
	ds_read_b32 v51, v9 offset:2048
	v_add_u32_e32 v9, v8, v9
	ds_read_b32 v27, v9
	ds_read_b32 v52, v9 offset:2048
	v_add_u32_e32 v9, v8, v9
	ds_read_b32 v28, v9
	ds_read_b32 v53, v9 offset:2048
	v_add_u32_e32 v9, v8, v9
	ds_read_b32 v29, v9
	ds_read_b32 v54, v9 offset:2048
	v_add_u32_e32 v9, v8, v9
	ds_read_b32 v30, v9
	ds_read_b32 v55, v9 offset:2048
	v_add_u32_e32 v9, v8, v9
	ds_read_b32 v31, v9
	ds_read_b32 v56, v9 offset:2048
	v_add_u32_e32 v9, v8, v9
	ds_read_b32 v32, v9
	ds_read_b32 v57, v9 offset:2048
	v_add_u32_e32 v9, v8, v9
	ds_read_b32 v33, v9
	ds_read_b32 v58, v9 offset:2048
	v_add_u32_e32 v9, v8, v9
	ds_read_b32 v34, v9
	ds_read_b32 v59, v9 offset:2048
	v_add_u32_e32 v9, v8, v9
	ds_read_b32 v35, v9
	ds_read_b32 v60, v9 offset:2048
	v_add_u32_e32 v9, v8, v9
	s_waitcnt lgkmcnt(0)
	v_add_f32_e32 v1, v1, v20
	ds_write_b32 v18, v1
	global_store_dword v[12:13], v1, off
	v_sub_f32_e32 v45, v45, v1
	global_store_dword v[14:15], v45, off
	v_add_u32_e32 v18, v8, v18
	v_lshl_add_u64 v[12:13], v[12:13], 0, v[16:17]
	v_lshl_add_u64 v[14:15], v[14:15], 0, v[16:17]
	v_add_f32_e32 v1, v1, v21
	ds_write_b32 v18, v1
	global_store_dword v[12:13], v1, off
	v_sub_f32_e32 v46, v46, v1
	global_store_dword v[14:15], v46, off
	v_add_u32_e32 v18, v8, v18
	v_lshl_add_u64 v[12:13], v[12:13], 0, v[16:17]
	v_lshl_add_u64 v[14:15], v[14:15], 0, v[16:17]
	v_add_f32_e32 v1, v1, v22
	ds_write_b32 v18, v1
	global_store_dword v[12:13], v1, off
	v_sub_f32_e32 v47, v47, v1
	global_store_dword v[14:15], v47, off
	v_add_u32_e32 v18, v8, v18
	v_lshl_add_u64 v[12:13], v[12:13], 0, v[16:17]
	v_lshl_add_u64 v[14:15], v[14:15], 0, v[16:17]
	v_add_f32_e32 v1, v1, v23
	ds_write_b32 v18, v1
	global_store_dword v[12:13], v1, off
	v_sub_f32_e32 v48, v48, v1
	global_store_dword v[14:15], v48, off
	v_add_u32_e32 v18, v8, v18
	v_lshl_add_u64 v[12:13], v[12:13], 0, v[16:17]
	v_lshl_add_u64 v[14:15], v[14:15], 0, v[16:17]
	v_add_f32_e32 v1, v1, v24
	ds_write_b32 v18, v1
	global_store_dword v[12:13], v1, off
	v_sub_f32_e32 v49, v49, v1
	global_store_dword v[14:15], v49, off
	v_add_u32_e32 v18, v8, v18
	v_lshl_add_u64 v[12:13], v[12:13], 0, v[16:17]
	v_lshl_add_u64 v[14:15], v[14:15], 0, v[16:17]
	v_add_f32_e32 v1, v1, v25
	ds_write_b32 v18, v1
	global_store_dword v[12:13], v1, off
	v_sub_f32_e32 v50, v50, v1
; DI void mlstm_prep_item(const KP& P, int layer, int b, int tb, LAS unsigned char* lds) {
;     ...
;         for (int step = 0; step < 64; ++step) { const int t = dir ? 63 - step : step;
;             run += Fl[tid * 64 + t]; Fl[tid * 64 + t] = run; FG[(R0 + t) * 8 + tid] = run; IG[(R0 + t) * 8 + tid] = Il[tid * 64 + t] - run; } }
	global_store_dword v[14:15], v50, off
	v_add_u32_e32 v18, v8, v18
	v_lshl_add_u64 v[12:13], v[12:13], 0, v[16:17]
	v_lshl_add_u64 v[14:15], v[14:15], 0, v[16:17]
	v_add_f32_e32 v1, v1, v26
	ds_write_b32 v18, v1
	global_store_dword v[12:13], v1, off
	v_sub_f32_e32 v51, v51, v1
	global_store_dword v[14:15], v51, off
	v_add_u32_e32 v18, v8, v18
	v_lshl_add_u64 v[12:13], v[12:13], 0, v[16:17]
	v_lshl_add_u64 v[14:15], v[14:15], 0, v[16:17]
	v_add_f32_e32 v1, v1, v27
	ds_write_b32 v18, v1
	global_store_dword v[12:13], v1, off
	v_sub_f32_e32 v52, v52, v1
	global_store_dword v[14:15], v52, off
	v_add_u32_e32 v18, v8, v18
	v_lshl_add_u64 v[12:13], v[12:13], 0, v[16:17]
	v_lshl_add_u64 v[14:15], v[14:15], 0, v[16:17]
	v_add_f32_e32 v1, v1, v28
	ds_write_b32 v18, v1
	global_store_dword v[12:13], v1, off
	v_sub_f32_e32 v53, v53, v1
	global_store_dword v[14:15], v53, off
	v_add_u32_e32 v18, v8, v18
	v_lshl_add_u64 v[12:13], v[12:13], 0, v[16:17]
	v_lshl_add_u64 v[14:15], v[14:15], 0, v[16:17]
	v_add_f32_e32 v1, v1, v29
	ds_write_b32 v18, v1
	global_store_dword v[12:13], v1, off
	v_sub_f32_e32 v54, v54, v1
	global_store_dword v[14:15], v54, off
	v_add_u32_e32 v18, v8, v18
	v_lshl_add_u64 v[12:13], v[12:13], 0, v[16:17]
	v_lshl_add_u64 v[14:15], v[14:15], 0, v[16:17]
	v_add_f32_e32 v1, v1, v30
	ds_write_b32 v18, v1
	global_store_dword v[12:13], v1, off
	v_sub_f32_e32 v55, v55, v1
	global_store_dword v[14:15], v55, off
	v_add_u32_e32 v18, v8, v18
	v_lshl_add_u64 v[12:13], v[12:13], 0, v[16:17]
	v_lshl_add_u64 v[14:15], v[14:15], 0, v[16:17]
	v_add_f32_e32 v1, v1, v31
	ds_write_b32 v18, v1
	global_store_dword v[12:13], v1, off
	v_sub_f32_e32 v56, v56, v1
	global_store_dword v[14:15], v56, off
	v_add_u32_e32 v18, v8, v18
	v_lshl_add_u64 v[12:13], v[12:13], 0, v[16:17]
	v_lshl_add_u64 v[14:15], v[14:15], 0, v[16:17]
	v_add_f32_e32 v1, v1, v32
	ds_write_b32 v18, v1
	global_store_dword v[12:13], v1, off
	v_sub_f32_e32 v57, v57, v1
	global_store_dword v[14:15], v57, off
	v_add_u32_e32 v18, v8, v18
	v_lshl_add_u64 v[12:13], v[12:13], 0, v[16:17]
	v_lshl_add_u64 v[14:15], v[14:15], 0, v[16:17]
	v_add_f32_e32 v1, v1, v33
	ds_write_b32 v18, v1
	global_store_dword v[12:13], v1, off
	v_sub_f32_e32 v58, v58, v1
	global_store_dword v[14:15], v58, off
	v_add_u32_e32 v18, v8, v18
	v_lshl_add_u64 v[12:13], v[12:13], 0, v[16:17]
	v_lshl_add_u64 v[14:15], v[14:15], 0, v[16:17]
	v_add_f32_e32 v1, v1, v34
	ds_write_b32 v18, v1
	global_store_dword v[12:13], v1, off
	v_sub_f32_e32 v59, v59, v1
	global_store_dword v[14:15], v59, off
	v_add_u32_e32 v18, v8, v18
	v_lshl_add_u64 v[12:13], v[12:13], 0, v[16:17]
	v_lshl_add_u64 v[14:15], v[14:15], 0, v[16:17]
	v_add_f32_e32 v1, v1, v35
	ds_write_b32 v18, v1
	global_store_dword v[12:13], v1, off
	v_sub_f32_e32 v60, v60, v1
	global_store_dword v[14:15], v60, off
	v_add_u32_e32 v18, v8, v18
	v_lshl_add_u64 v[12:13], v[12:13], 0, v[16:17]
	v_lshl_add_u64 v[14:15], v[14:15], 0, v[16:17]
	ds_read_b32 v20, v9
	ds_read_b32 v45, v9 offset:2048
	v_add_u32_e32 v9, v8, v9
	ds_read_b32 v21, v9
	ds_read_b32 v46, v9 offset:2048
	v_add_u32_e32 v9, v8, v9
	ds_read_b32 v22, v9
	ds_read_b32 v47, v9 offset:2048
	v_add_u32_e32 v9, v8, v9
	ds_read_b32 v23, v9
	ds_read_b32 v48, v9 offset:2048
	v_add_u32_e32 v9, v8, v9
	ds_read_b32 v24, v9
	ds_read_b32 v49, v9 offset:2048
	v_add_u32_e32 v9, v8, v9
	ds_read_b32 v25, v9
	ds_read_b32 v50, v9 offset:2048
	v_add_u32_e32 v9, v8, v9
	ds_read_b32 v26, v9
	ds_read_b32 v51, v9 offset:2048
	v_add_u32_e32 v9, v8, v9
	ds_read_b32 v27, v9
	ds_read_b32 v52, v9 offset:2048
	v_add_u32_e32 v9, v8, v9
	ds_read_b32 v28, v9
	ds_read_b32 v53, v9 offset:2048
	v_add_u32_e32 v9, v8, v9
	ds_read_b32 v29, v9
	ds_read_b32 v54, v9 offset:2048
	v_add_u32_e32 v9, v8, v9
	ds_read_b32 v30, v9
	ds_read_b32 v55, v9 offset:2048
	v_add_u32_e32 v9, v8, v9
	ds_read_b32 v31, v9
	ds_read_b32 v56, v9 offset:2048
	v_add_u32_e32 v9, v8, v9
	ds_read_b32 v32, v9
	ds_read_b32 v57, v9 offset:2048
	v_add_u32_e32 v9, v8, v9
	ds_read_b32 v33, v9
	ds_read_b32 v58, v9 offset:2048
	v_add_u32_e32 v9, v8, v9
	ds_read_b32 v34, v9
	ds_read_b32 v59, v9 offset:2048
	v_add_u32_e32 v9, v8, v9
	ds_read_b32 v35, v9
	ds_read_b32 v60, v9 offset:2048
	v_add_u32_e32 v9, v8, v9
	s_waitcnt lgkmcnt(0)
; DI void mlstm_prep_item(const KP& P, int layer, int b, int tb, LAS unsigned char* lds) {
;     ...
;         for (int step = 0; step < 64; ++step) { const int t = dir ? 63 - step : step;
;             run += Fl[tid * 64 + t]; Fl[tid * 64 + t] = run; FG[(R0 + t) * 8 + tid] = run; IG[(R0 + t) * 8 + tid] = Il[tid * 64 + t] - run; } }
	v_add_f32_e32 v1, v1, v20
	ds_write_b32 v18, v1
	global_store_dword v[12:13], v1, off
	v_sub_f32_e32 v45, v45, v1
	global_store_dword v[14:15], v45, off
	v_add_u32_e32 v18, v8, v18
	v_lshl_add_u64 v[12:13], v[12:13], 0, v[16:17]
	v_lshl_add_u64 v[14:15], v[14:15], 0, v[16:17]
	v_add_f32_e32 v1, v1, v21
	ds_write_b32 v18, v1
	global_store_dword v[12:13], v1, off
	v_sub_f32_e32 v46, v46, v1
	global_store_dword v[14:15], v46, off
	v_add_u32_e32 v18, v8, v18
	v_lshl_add_u64 v[12:13], v[12:13], 0, v[16:17]
	v_lshl_add_u64 v[14:15], v[14:15], 0, v[16:17]
	v_add_f32_e32 v1, v1, v22
	ds_write_b32 v18, v1
	global_store_dword v[12:13], v1, off
	v_sub_f32_e32 v47, v47, v1
	global_store_dword v[14:15], v47, off
	v_add_u32_e32 v18, v8, v18
	v_lshl_add_u64 v[12:13], v[12:13], 0, v[16:17]
	v_lshl_add_u64 v[14:15], v[14:15], 0, v[16:17]
	v_add_f32_e32 v1, v1, v23
	ds_write_b32 v18, v1
	global_store_dword v[12:13], v1, off
	v_sub_f32_e32 v48, v48, v1
	global_store_dword v[14:15], v48, off
	v_add_u32_e32 v18, v8, v18
	v_lshl_add_u64 v[12:13], v[12:13], 0, v[16:17]
	v_lshl_add_u64 v[14:15], v[14:15], 0, v[16:17]
	v_add_f32_e32 v1, v1, v24
	ds_write_b32 v18, v1
	global_store_dword v[12:13], v1, off
	v_sub_f32_e32 v49, v49, v1
	global_store_dword v[14:15], v49, off
	v_add_u32_e32 v18, v8, v18
	v_lshl_add_u64 v[12:13], v[12:13], 0, v[16:17]
	v_lshl_add_u64 v[14:15], v[14:15], 0, v[16:17]
	v_add_f32_e32 v1, v1, v25
	ds_write_b32 v18, v1
	global_store_dword v[12:13], v1, off
	v_sub_f32_e32 v50, v50, v1
	global_store_dword v[14:15], v50, off
	v_add_u32_e32 v18, v8, v18
	v_lshl_add_u64 v[12:13], v[12:13], 0, v[16:17]
	v_lshl_add_u64 v[14:15], v[14:15], 0, v[16:17]
	v_add_f32_e32 v1, v1, v26
	ds_write_b32 v18, v1
	global_store_dword v[12:13], v1, off
	v_sub_f32_e32 v51, v51, v1
	global_store_dword v[14:15], v51, off
	v_add_u32_e32 v18, v8, v18
	v_lshl_add_u64 v[12:13], v[12:13], 0, v[16:17]
	v_lshl_add_u64 v[14:15], v[14:15], 0, v[16:17]
	v_add_f32_e32 v1, v1, v27
	ds_write_b32 v18, v1
	global_store_dword v[12:13], v1, off
	v_sub_f32_e32 v52, v52, v1
	global_store_dword v[14:15], v52, off
	v_add_u32_e32 v18, v8, v18
	v_lshl_add_u64 v[12:13], v[12:13], 0, v[16:17]
	v_lshl_add_u64 v[14:15], v[14:15], 0, v[16:17]
	v_add_f32_e32 v1, v1, v28
	ds_write_b32 v18, v1
	global_store_dword v[12:13], v1, off
	v_sub_f32_e32 v53, v53, v1
	global_store_dword v[14:15], v53, off
	v_add_u32_e32 v18, v8, v18
	v_lshl_add_u64 v[12:13], v[12:13], 0, v[16:17]
	v_lshl_add_u64 v[14:15], v[14:15], 0, v[16:17]
	v_add_f32_e32 v1, v1, v29
	ds_write_b32 v18, v1
	global_store_dword v[12:13], v1, off
	v_sub_f32_e32 v54, v54, v1
	global_store_dword v[14:15], v54, off
	v_add_u32_e32 v18, v8, v18
	v_lshl_add_u64 v[12:13], v[12:13], 0, v[16:17]
	v_lshl_add_u64 v[14:15], v[14:15], 0, v[16:17]
	v_add_f32_e32 v1, v1, v30
	ds_write_b32 v18, v1
	global_store_dword v[12:13], v1, off
	v_sub_f32_e32 v55, v55, v1
	global_store_dword v[14:15], v55, off
	v_add_u32_e32 v18, v8, v18
	v_lshl_add_u64 v[12:13], v[12:13], 0, v[16:17]
	v_lshl_add_u64 v[14:15], v[14:15], 0, v[16:17]
	v_add_f32_e32 v1, v1, v31
	ds_write_b32 v18, v1
	global_store_dword v[12:13], v1, off
	v_sub_f32_e32 v56, v56, v1
	global_store_dword v[14:15], v56, off
	v_add_u32_e32 v18, v8, v18
	v_lshl_add_u64 v[12:13], v[12:13], 0, v[16:17]
	v_lshl_add_u64 v[14:15], v[14:15], 0, v[16:17]
	v_add_f32_e32 v1, v1, v32
	ds_write_b32 v18, v1
	global_store_dword v[12:13], v1, off
	v_sub_f32_e32 v57, v57, v1
	global_store_dword v[14:15], v57, off
	v_add_u32_e32 v18, v8, v18
	v_lshl_add_u64 v[12:13], v[12:13], 0, v[16:17]
	v_lshl_add_u64 v[14:15], v[14:15], 0, v[16:17]
	v_add_f32_e32 v1, v1, v33
	ds_write_b32 v18, v1
	global_store_dword v[12:13], v1, off
	v_sub_f32_e32 v58, v58, v1
	global_store_dword v[14:15], v58, off
	v_add_u32_e32 v18, v8, v18
	v_lshl_add_u64 v[12:13], v[12:13], 0, v[16:17]
	v_lshl_add_u64 v[14:15], v[14:15], 0, v[16:17]
	v_add_f32_e32 v1, v1, v34
	ds_write_b32 v18, v1
	global_store_dword v[12:13], v1, off
	v_sub_f32_e32 v59, v59, v1
	global_store_dword v[14:15], v59, off
	v_add_u32_e32 v18, v8, v18
	v_lshl_add_u64 v[12:13], v[12:13], 0, v[16:17]
	v_lshl_add_u64 v[14:15], v[14:15], 0, v[16:17]
	v_add_f32_e32 v1, v1, v35
	ds_write_b32 v18, v1
	global_store_dword v[12:13], v1, off
	v_sub_f32_e32 v60, v60, v1
	global_store_dword v[14:15], v60, off
	v_add_u32_e32 v18, v8, v18
	v_lshl_add_u64 v[12:13], v[12:13], 0, v[16:17]
	v_lshl_add_u64 v[14:15], v[14:15], 0, v[16:17]
	ds_read_b32 v20, v9
	ds_read_b32 v45, v9 offset:2048
	v_add_u32_e32 v9, v8, v9
	ds_read_b32 v21, v9
	ds_read_b32 v46, v9 offset:2048
	v_add_u32_e32 v9, v8, v9
	ds_read_b32 v22, v9
	ds_read_b32 v47, v9 offset:2048
	v_add_u32_e32 v9, v8, v9
	ds_read_b32 v23, v9
	ds_read_b32 v48, v9 offset:2048
	v_add_u32_e32 v9, v8, v9
	ds_read_b32 v24, v9
	ds_read_b32 v49, v9 offset:2048
	v_add_u32_e32 v9, v8, v9
	ds_read_b32 v25, v9
	ds_read_b32 v50, v9 offset:2048
	v_add_u32_e32 v9, v8, v9
	ds_read_b32 v26, v9
	ds_read_b32 v51, v9 offset:2048
	v_add_u32_e32 v9, v8, v9
	ds_read_b32 v27, v9
	ds_read_b32 v52, v9 offset:2048
	v_add_u32_e32 v9, v8, v9
	ds_read_b32 v28, v9
	ds_read_b32 v53, v9 offset:2048
	v_add_u32_e32 v9, v8, v9
	ds_read_b32 v29, v9
	ds_read_b32 v54, v9 offset:2048
	v_add_u32_e32 v9, v8, v9
	ds_read_b32 v30, v9
	ds_read_b32 v55, v9 offset:2048
	v_add_u32_e32 v9, v8, v9
	ds_read_b32 v31, v9
	ds_read_b32 v56, v9 offset:2048
	v_add_u32_e32 v9, v8, v9
	ds_read_b32 v32, v9
	ds_read_b32 v57, v9 offset:2048
	v_add_u32_e32 v9, v8, v9
	ds_read_b32 v33, v9
	ds_read_b32 v58, v9 offset:2048
	v_add_u32_e32 v9, v8, v9
	ds_read_b32 v34, v9
	ds_read_b32 v59, v9 offset:2048
	v_add_u32_e32 v9, v8, v9
	ds_read_b32 v35, v9
	ds_read_b32 v60, v9 offset:2048
	v_add_u32_e32 v9, v8, v9
	s_waitcnt lgkmcnt(0)
; DI void mlstm_prep_item(const KP& P, int layer, int b, int tb, LAS unsigned char* lds) {
;     ...
;         for (int step = 0; step < 64; ++step) { const int t = dir ? 63 - step : step;
;             run += Fl[tid * 64 + t]; Fl[tid * 64 + t] = run; FG[(R0 + t) * 8 + tid] = run; IG[(R0 + t) * 8 + tid] = Il[tid * 64 + t] - run; } }
	v_add_f32_e32 v1, v1, v20
	ds_write_b32 v18, v1
	global_store_dword v[12:13], v1, off
	v_sub_f32_e32 v45, v45, v1
	global_store_dword v[14:15], v45, off
	v_add_u32_e32 v18, v8, v18
	v_lshl_add_u64 v[12:13], v[12:13], 0, v[16:17]
	v_lshl_add_u64 v[14:15], v[14:15], 0, v[16:17]
	v_add_f32_e32 v1, v1, v21
	ds_write_b32 v18, v1
	global_store_dword v[12:13], v1, off
	v_sub_f32_e32 v46, v46, v1
	global_store_dword v[14:15], v46, off
	v_add_u32_e32 v18, v8, v18
	v_lshl_add_u64 v[12:13], v[12:13], 0, v[16:17]
	v_lshl_add_u64 v[14:15], v[14:15], 0, v[16:17]
	v_add_f32_e32 v1, v1, v22
	ds_write_b32 v18, v1
	global_store_dword v[12:13], v1, off
	v_sub_f32_e32 v47, v47, v1
	global_store_dword v[14:15], v47, off
	v_add_u32_e32 v18, v8, v18
	v_lshl_add_u64 v[12:13], v[12:13], 0, v[16:17]
	v_lshl_add_u64 v[14:15], v[14:15], 0, v[16:17]
	v_add_f32_e32 v1, v1, v23
	ds_write_b32 v18, v1
	global_store_dword v[12:13], v1, off
	v_sub_f32_e32 v48, v48, v1
	global_store_dword v[14:15], v48, off
	v_add_u32_e32 v18, v8, v18
	v_lshl_add_u64 v[12:13], v[12:13], 0, v[16:17]
	v_lshl_add_u64 v[14:15], v[14:15], 0, v[16:17]
	v_add_f32_e32 v1, v1, v24
	ds_write_b32 v18, v1
	global_store_dword v[12:13], v1, off
	v_sub_f32_e32 v49, v49, v1
	global_store_dword v[14:15], v49, off
	v_add_u32_e32 v18, v8, v18
	v_lshl_add_u64 v[12:13], v[12:13], 0, v[16:17]
	v_lshl_add_u64 v[14:15], v[14:15], 0, v[16:17]
	v_add_f32_e32 v1, v1, v25
	ds_write_b32 v18, v1
	global_store_dword v[12:13], v1, off
	v_sub_f32_e32 v50, v50, v1
	global_store_dword v[14:15], v50, off
	v_add_u32_e32 v18, v8, v18
	v_lshl_add_u64 v[12:13], v[12:13], 0, v[16:17]
	v_lshl_add_u64 v[14:15], v[14:15], 0, v[16:17]
	v_add_f32_e32 v1, v1, v26
	ds_write_b32 v18, v1
	global_store_dword v[12:13], v1, off
	v_sub_f32_e32 v51, v51, v1
	global_store_dword v[14:15], v51, off
	v_add_u32_e32 v18, v8, v18
	v_lshl_add_u64 v[12:13], v[12:13], 0, v[16:17]
	v_lshl_add_u64 v[14:15], v[14:15], 0, v[16:17]
	v_add_f32_e32 v1, v1, v27
	ds_write_b32 v18, v1
	global_store_dword v[12:13], v1, off
	v_sub_f32_e32 v52, v52, v1
	global_store_dword v[14:15], v52, off
	v_add_u32_e32 v18, v8, v18
	v_lshl_add_u64 v[12:13], v[12:13], 0, v[16:17]
	v_lshl_add_u64 v[14:15], v[14:15], 0, v[16:17]
	v_add_f32_e32 v1, v1, v28
	ds_write_b32 v18, v1
	global_store_dword v[12:13], v1, off
	v_sub_f32_e32 v53, v53, v1
	global_store_dword v[14:15], v53, off
	v_add_u32_e32 v18, v8, v18
	v_lshl_add_u64 v[12:13], v[12:13], 0, v[16:17]
	v_lshl_add_u64 v[14:15], v[14:15], 0, v[16:17]
	v_add_f32_e32 v1, v1, v29
	ds_write_b32 v18, v1
	global_store_dword v[12:13], v1, off
	v_sub_f32_e32 v54, v54, v1
	global_store_dword v[14:15], v54, off
	v_add_u32_e32 v18, v8, v18
	v_lshl_add_u64 v[12:13], v[12:13], 0, v[16:17]
	v_lshl_add_u64 v[14:15], v[14:15], 0, v[16:17]
	v_add_f32_e32 v1, v1, v30
	ds_write_b32 v18, v1
	global_store_dword v[12:13], v1, off
	v_sub_f32_e32 v55, v55, v1
	global_store_dword v[14:15], v55, off
	v_add_u32_e32 v18, v8, v18
	v_lshl_add_u64 v[12:13], v[12:13], 0, v[16:17]
	v_lshl_add_u64 v[14:15], v[14:15], 0, v[16:17]
	v_add_f32_e32 v1, v1, v31
	ds_write_b32 v18, v1
	global_store_dword v[12:13], v1, off
	v_sub_f32_e32 v56, v56, v1
	global_store_dword v[14:15], v56, off
	v_add_u32_e32 v18, v8, v18
	v_lshl_add_u64 v[12:13], v[12:13], 0, v[16:17]
	v_lshl_add_u64 v[14:15], v[14:15], 0, v[16:17]
	v_add_f32_e32 v1, v1, v32
	ds_write_b32 v18, v1
	global_store_dword v[12:13], v1, off
	v_sub_f32_e32 v57, v57, v1
	global_store_dword v[14:15], v57, off
	v_add_u32_e32 v18, v8, v18
	v_lshl_add_u64 v[12:13], v[12:13], 0, v[16:17]
	v_lshl_add_u64 v[14:15], v[14:15], 0, v[16:17]
	v_add_f32_e32 v1, v1, v33
	ds_write_b32 v18, v1
	global_store_dword v[12:13], v1, off
	v_sub_f32_e32 v58, v58, v1
	global_store_dword v[14:15], v58, off
	v_add_u32_e32 v18, v8, v18
	v_lshl_add_u64 v[12:13], v[12:13], 0, v[16:17]
	v_lshl_add_u64 v[14:15], v[14:15], 0, v[16:17]
	v_add_f32_e32 v1, v1, v34
	ds_write_b32 v18, v1
	global_store_dword v[12:13], v1, off
	v_sub_f32_e32 v59, v59, v1
	global_store_dword v[14:15], v59, off
	v_add_u32_e32 v18, v8, v18
	v_lshl_add_u64 v[12:13], v[12:13], 0, v[16:17]
	v_lshl_add_u64 v[14:15], v[14:15], 0, v[16:17]
	v_add_f32_e32 v1, v1, v35
	ds_write_b32 v18, v1
	global_store_dword v[12:13], v1, off
	v_sub_f32_e32 v60, v60, v1
	global_store_dword v[14:15], v60, off
	v_add_u32_e32 v18, v8, v18
	v_lshl_add_u64 v[12:13], v[12:13], 0, v[16:17]
	v_lshl_add_u64 v[14:15], v[14:15], 0, v[16:17]
	ds_read_b32 v20, v9
	ds_read_b32 v45, v9 offset:2048
	v_add_u32_e32 v9, v8, v9
	ds_read_b32 v21, v9
	ds_read_b32 v46, v9 offset:2048
	v_add_u32_e32 v9, v8, v9
	ds_read_b32 v22, v9
	ds_read_b32 v47, v9 offset:2048
	v_add_u32_e32 v9, v8, v9
	ds_read_b32 v23, v9
	ds_read_b32 v48, v9 offset:2048
	v_add_u32_e32 v9, v8, v9
	ds_read_b32 v24, v9
	ds_read_b32 v49, v9 offset:2048
	v_add_u32_e32 v9, v8, v9
	ds_read_b32 v25, v9
	ds_read_b32 v50, v9 offset:2048
	v_add_u32_e32 v9, v8, v9
	ds_read_b32 v26, v9
	ds_read_b32 v51, v9 offset:2048
	v_add_u32_e32 v9, v8, v9
	ds_read_b32 v27, v9
	ds_read_b32 v52, v9 offset:2048
	v_add_u32_e32 v9, v8, v9
	ds_read_b32 v28, v9
	ds_read_b32 v53, v9 offset:2048
	v_add_u32_e32 v9, v8, v9
	ds_read_b32 v29, v9
	ds_read_b32 v54, v9 offset:2048
	v_add_u32_e32 v9, v8, v9
	ds_read_b32 v30, v9
	ds_read_b32 v55, v9 offset:2048
	v_add_u32_e32 v9, v8, v9
	ds_read_b32 v31, v9
	ds_read_b32 v56, v9 offset:2048
	v_add_u32_e32 v9, v8, v9
	ds_read_b32 v32, v9
	ds_read_b32 v57, v9 offset:2048
	v_add_u32_e32 v9, v8, v9
	ds_read_b32 v33, v9
	ds_read_b32 v58, v9 offset:2048
	v_add_u32_e32 v9, v8, v9
	ds_read_b32 v34, v9
	ds_read_b32 v59, v9 offset:2048
	v_add_u32_e32 v9, v8, v9
	ds_read_b32 v35, v9
	ds_read_b32 v60, v9 offset:2048
	v_add_u32_e32 v9, v8, v9
	s_waitcnt lgkmcnt(0)
; DI void mlstm_prep_item(const KP& P, int layer, int b, int tb, LAS unsigned char* lds) {
;     ...
;         for (int step = 0; step < 64; ++step) { const int t = dir ? 63 - step : step;
;             run += Fl[tid * 64 + t]; Fl[tid * 64 + t] = run; FG[(R0 + t) * 8 + tid] = run; IG[(R0 + t) * 8 + tid] = Il[tid * 64 + t] - run; } }
	v_add_f32_e32 v1, v1, v20
	ds_write_b32 v18, v1
	global_store_dword v[12:13], v1, off
	v_sub_f32_e32 v45, v45, v1
	global_store_dword v[14:15], v45, off
	v_add_u32_e32 v18, v8, v18
	v_lshl_add_u64 v[12:13], v[12:13], 0, v[16:17]
	v_lshl_add_u64 v[14:15], v[14:15], 0, v[16:17]
	v_add_f32_e32 v1, v1, v21
	ds_write_b32 v18, v1
	global_store_dword v[12:13], v1, off
	v_sub_f32_e32 v46, v46, v1
	global_store_dword v[14:15], v46, off
	v_add_u32_e32 v18, v8, v18
	v_lshl_add_u64 v[12:13], v[12:13], 0, v[16:17]
	v_lshl_add_u64 v[14:15], v[14:15], 0, v[16:17]
	v_add_f32_e32 v1, v1, v22
	ds_write_b32 v18, v1
	global_store_dword v[12:13], v1, off
	v_sub_f32_e32 v47, v47, v1
	global_store_dword v[14:15], v47, off
	v_add_u32_e32 v18, v8, v18
	v_lshl_add_u64 v[12:13], v[12:13], 0, v[16:17]
	v_lshl_add_u64 v[14:15], v[14:15], 0, v[16:17]
	v_add_f32_e32 v1, v1, v23
	ds_write_b32 v18, v1
	global_store_dword v[12:13], v1, off
	v_sub_f32_e32 v48, v48, v1
	global_store_dword v[14:15], v48, off
	v_add_u32_e32 v18, v8, v18
	v_lshl_add_u64 v[12:13], v[12:13], 0, v[16:17]
	v_lshl_add_u64 v[14:15], v[14:15], 0, v[16:17]
	v_add_f32_e32 v1, v1, v24
	ds_write_b32 v18, v1
	global_store_dword v[12:13], v1, off
	v_sub_f32_e32 v49, v49, v1
	global_store_dword v[14:15], v49, off
	v_add_u32_e32 v18, v8, v18
	v_lshl_add_u64 v[12:13], v[12:13], 0, v[16:17]
	v_lshl_add_u64 v[14:15], v[14:15], 0, v[16:17]
	v_add_f32_e32 v1, v1, v25
	ds_write_b32 v18, v1
	global_store_dword v[12:13], v1, off
	v_sub_f32_e32 v50, v50, v1
	global_store_dword v[14:15], v50, off
	v_add_u32_e32 v18, v8, v18
	v_lshl_add_u64 v[12:13], v[12:13], 0, v[16:17]
	v_lshl_add_u64 v[14:15], v[14:15], 0, v[16:17]
	v_add_f32_e32 v1, v1, v26
	ds_write_b32 v18, v1
	global_store_dword v[12:13], v1, off
	v_sub_f32_e32 v51, v51, v1
	global_store_dword v[14:15], v51, off
	v_add_u32_e32 v18, v8, v18
	v_lshl_add_u64 v[12:13], v[12:13], 0, v[16:17]
	v_lshl_add_u64 v[14:15], v[14:15], 0, v[16:17]
	v_add_f32_e32 v1, v1, v27
	ds_write_b32 v18, v1
	global_store_dword v[12:13], v1, off
	v_sub_f32_e32 v52, v52, v1
	global_store_dword v[14:15], v52, off
	v_add_u32_e32 v18, v8, v18
	v_lshl_add_u64 v[12:13], v[12:13], 0, v[16:17]
	v_lshl_add_u64 v[14:15], v[14:15], 0, v[16:17]
	v_add_f32_e32 v1, v1, v28
	ds_write_b32 v18, v1
	global_store_dword v[12:13], v1, off
	v_sub_f32_e32 v53, v53, v1
	global_store_dword v[14:15], v53, off
	v_add_u32_e32 v18, v8, v18
	v_lshl_add_u64 v[12:13], v[12:13], 0, v[16:17]
	v_lshl_add_u64 v[14:15], v[14:15], 0, v[16:17]
	v_add_f32_e32 v1, v1, v29
	ds_write_b32 v18, v1
	global_store_dword v[12:13], v1, off
	v_sub_f32_e32 v54, v54, v1
	global_store_dword v[14:15], v54, off
	v_add_u32_e32 v18, v8, v18
	v_lshl_add_u64 v[12:13], v[12:13], 0, v[16:17]
	v_lshl_add_u64 v[14:15], v[14:15], 0, v[16:17]
	v_add_f32_e32 v1, v1, v30
	ds_write_b32 v18, v1
	global_store_dword v[12:13], v1, off
	v_sub_f32_e32 v55, v55, v1
	global_store_dword v[14:15], v55, off
	v_add_u32_e32 v18, v8, v18
	v_lshl_add_u64 v[12:13], v[12:13], 0, v[16:17]
	v_lshl_add_u64 v[14:15], v[14:15], 0, v[16:17]
	v_add_f32_e32 v1, v1, v31
	ds_write_b32 v18, v1
	global_store_dword v[12:13], v1, off
	v_sub_f32_e32 v56, v56, v1
	global_store_dword v[14:15], v56, off
	v_add_u32_e32 v18, v8, v18
	v_lshl_add_u64 v[12:13], v[12:13], 0, v[16:17]
	v_lshl_add_u64 v[14:15], v[14:15], 0, v[16:17]
	v_add_f32_e32 v1, v1, v32
	ds_write_b32 v18, v1
	global_store_dword v[12:13], v1, off
	v_sub_f32_e32 v57, v57, v1
	global_store_dword v[14:15], v57, off
	v_add_u32_e32 v18, v8, v18
	v_lshl_add_u64 v[12:13], v[12:13], 0, v[16:17]
	v_lshl_add_u64 v[14:15], v[14:15], 0, v[16:17]
	v_add_f32_e32 v1, v1, v33
	ds_write_b32 v18, v1
	global_store_dword v[12:13], v1, off
	v_sub_f32_e32 v58, v58, v1
	global_store_dword v[14:15], v58, off
	v_add_u32_e32 v18, v8, v18
	v_lshl_add_u64 v[12:13], v[12:13], 0, v[16:17]
	v_lshl_add_u64 v[14:15], v[14:15], 0, v[16:17]
	v_add_f32_e32 v1, v1, v34
	ds_write_b32 v18, v1
	global_store_dword v[12:13], v1, off
	v_sub_f32_e32 v59, v59, v1
	global_store_dword v[14:15], v59, off
	v_add_u32_e32 v18, v8, v18
	v_lshl_add_u64 v[12:13], v[12:13], 0, v[16:17]
	v_lshl_add_u64 v[14:15], v[14:15], 0, v[16:17]
	v_add_f32_e32 v1, v1, v35
	ds_write_b32 v18, v1
	global_store_dword v[12:13], v1, off
	v_sub_f32_e32 v60, v60, v1
	global_store_dword v[14:15], v60, off
	v_add_u32_e32 v18, v8, v18
	v_lshl_add_u64 v[12:13], v[12:13], 0, v[16:17]
	v_lshl_add_u64 v[14:15], v[14:15], 0, v[16:17]

; DI int rot(int bx, int k, int G) { int r = bx + k; while (r >= G) r -= G; return r; }
; DI void prep_phase(const KP& P, int layer, LAS unsigned char* lds) {
;     ...
;     for (int it = blockIdx.x; it < NBT; it += G) mlstm_prep_item(P, layer, it / NTB, it % NTB, lds);
;     for (int it = rot((int)blockIdx.x, 224, G); it < NBT; it += G) gla_prep_item(P, layer, it / NTB, it % NTB, lds);
.LBB0_278:
	s_sub_i32 s4, s4, s0
	s_cmp_ge_i32 s4, s0
	s_cbranch_scc1 .LBB0_278
	s_cmpk_lt_i32 s4, 0x220
	v_readlane_b32 s7, v254, 28
	s_cbranch_scc0 .LBB0_288
	v_readlane_b32 s0, v254, 53
	s_lshl_b32 s5, s0, 12
	s_lshl_b32 s6, s0, 8
	v_readlane_b32 s1, v254, 54
	s_mov_b32 s97, 1
	s_branch .LBB0_282

; #define LAS __attribute__((address_space(3)))
; DI void gla_prep_item(const KP& P, int layer, int b, int tb, LAS unsigned char* lds) {
;     ...
;     { u32x4 kv[2], vv[4];
; #pragma unroll
;       for (int i = 0; i < 2; ++i) { const int q = tid + 512 * i, row = q >> 4, ch = q & 15; kv[i] = ldg16(Z + (R0 + row) * ZW + C_KC + ch * 8); }
; #pragma unroll
;       for (int i = 0; i < 4; ++i) { const int q = tid + 512 * i, row = q >> 5, ch = q & 31; vv[i] = ldg16(Z + (R0 + row) * ZW + C_VC + ch * 8); }
;       const int tok = tid >> 3, c4 = (tid & 7) * 4; const f32x4 gv = *(const f32x4*)(GATE + (R0 + tok) * 48 + c4);
; #pragma unroll
;       for (int i = 0; i < 2; ++i) { const int q = tid + 512 * i, row = q >> 4, ch = q & 15; *(LAS u32x4*)(Kt + row * KP_ + ch * 8) = kv[i]; }
; #pragma unroll
;       for (int i = 0; i < 4; ++i) { const int q = tid + 512 * i, row = q >> 5, ch = q & 31; *(LAS u32x4*)(Vt + row * VP + ch * 8) = vv[i]; }
;       *(LAS f32x4*)(Gt + tok * 32 + c4) = gv; }
;     __syncthreads();
;     float* BG = (float*)(P.ws + WS_BG);
;     { const int dc = tid & 255, dir = dc >> 7, ch = dc & 127;
;       float w[16];
; #pragma unroll
;       for (int k = 0; k < 16; ++k) w[k] = P.w_gla_gate[(((size_t)layer * 2 + dir) * 16 + k) * 128 + ch];
;       const float bias = P.b_gla_gate[(layer * 2 + dir) * 128 + ch];
.LBB0_282:
	s_mul_hi_i32 s0, s4, 0x78787879
	s_lshr_b32 s1, s0, 31
	s_ashr_i32 s8, s0, 5
	s_add_i32 s8, s8, s1
	s_mul_i32 s0, s8, 0x44
	s_sub_i32 s7, s4, s0
	v_readlane_b32 s0, v251, 4
	v_mbcnt_lo_u32_b32 v10, -1, 0
	v_mbcnt_hi_u32_b32 v10, -1, v10
	s_mul_i32 s2, s8, 0x1100
	s_mul_hi_i32 s1, s8, 0x1100
	v_add_u32_e32 v11, s0, v10
	s_lshl_b32 s0, s7, 6
	s_ashr_i32 s3, s0, 31
	s_add_u32 s0, s2, s0
	v_ashrrev_i32_e32 v8, 4, v11
	s_addc_u32 s1, s1, s3
	v_ashrrev_i32_e32 v9, 31, v8
	v_readlane_b32 s2, v253, 12
	v_lshl_add_u64 v[0:1], s[0:1], 0, v[8:9]
	v_readlane_b32 s3, v253, 13
	v_lshlrev_b32_e32 v9, 4, v10
	v_ashrrev_i32_e32 v34, 5, v11
	v_mov_b64_e32 v[20:21], s[2:3]
	s_movk_i32 s9, 0x1800
	v_and_b32_e32 v112, 0xf0, v9
	v_add_u32_e32 v16, 0x200, v11
	v_ashrrev_i32_e32 v35, 31, v34
	v_and_b32_e32 v36, 0x1f0, v9
	v_add_u32_e32 v9, 0x400, v11
	v_mad_u64_u32 v[2:3], s[2:3], v0, s9, v[20:21]
	v_ashrrev_i32_e32 v32, 4, v16
	v_lshl_add_u64 v[12:13], s[0:1], 0, v[34:35]
	v_ashrrev_i32_e32 v40, 5, v9
	v_mad_i32_i24 v3, v1, s9, v3
	v_ashrrev_i32_e32 v33, 31, v32
	v_mad_u64_u32 v[14:15], s[2:3], v12, s9, v[20:21]
	v_ashrrev_i32_e32 v38, 5, v16
	v_ashrrev_i32_e32 v41, 31, v40
	v_lshl_add_u64 v[0:1], v[2:3], 0, v[112:113]
	v_lshl_add_u64 v[2:3], s[0:1], 0, v[32:33]
	v_mad_i32_i24 v15, v13, s9, v15
	v_mov_b32_e32 v37, v113
	v_ashrrev_i32_e32 v39, 31, v38
	v_lshl_add_u64 v[22:23], s[0:1], 0, v[40:41]
	v_add_u32_e32 v9, 0x600, v11
	v_mad_u64_u32 v[4:5], s[2:3], v2, s9, v[20:21]
	v_lshl_add_u64 v[12:13], v[14:15], 0, v[36:37]
	v_lshl_add_u64 v[14:15], s[0:1], 0, v[38:39]
	v_mad_u64_u32 v[24:25], s[2:3], v22, s9, v[20:21]
	v_ashrrev_i32_e32 v42, 5, v9
	v_mad_i32_i24 v5, v3, s9, v5
	v_mad_u64_u32 v[16:17], s[2:3], v14, s9, v[20:21]
	v_mad_i32_i24 v25, v23, s9, v25
	v_ashrrev_i32_e32 v43, 31, v42
	v_lshl_add_u64 v[4:5], v[4:5], 0, v[112:113]
	v_mad_i32_i24 v17, v15, s9, v17
	v_lshl_add_u64 v[22:23], v[24:25], 0, v[36:37]
	v_lshl_add_u64 v[24:25], s[0:1], 0, v[42:43]
	v_ashrrev_i32_e32 v44, 3, v11
	global_load_dwordx4 v[0:3], v[0:1], off offset:2304
	s_nop 0
	global_load_dwordx4 v[4:7], v[4:5], off offset:2304
	v_lshl_add_u64 v[16:17], v[16:17], 0, v[36:37]
	v_mad_u64_u32 v[20:21], s[2:3], v24, s9, v[20:21]
	v_ashrrev_i32_e32 v45, 31, v44
	global_load_dwordx4 v[12:15], v[12:13], off offset:2560
	s_nop 0
	global_load_dwordx4 v[16:19], v[16:17], off offset:2560
	v_mad_i32_i24 v21, v25, s9, v21
	v_lshl_add_u64 v[28:29], s[0:1], 0, v[44:45]
	v_mov_b64_e32 v[30:31], s[28:29]
	s_movk_i32 s9, 0xc0
	v_lshl_add_u64 v[24:25], v[20:21], 0, v[36:37]
	v_mad_u64_u32 v[30:31], s[2:3], v28, s9, v[30:31]
	v_lshlrev_b32_e32 v9, 4, v11
	global_load_dwordx4 v[20:23], v[22:23], off offset:2560
	s_nop 0
	global_load_dwordx4 v[24:27], v[24:25], off offset:2560
	v_mad_i32_i24 v31, v29, s9, v31
	v_and_b32_e32 v46, 0x70, v9
	v_mov_b32_e32 v47, v113
	v_lshl_add_u64 v[28:29], v[30:31], 0, v[46:47]
	global_load_dwordx4 v[28:31], v[28:29], off
	v_add_u32_e32 v48, 0, v112
	s_movk_i32 s9, 0x120
	v_add_u32_e32 v36, 0, v36
	v_mad_u64_u32 v[8:9], s[2:3], v8, s9, v[48:49]
	v_mad_u64_u32 v[32:33], s[2:3], v32, s9, v[48:49]
	s_movk_i32 s9, 0x220
	v_mad_u64_u32 v[34:35], s[2:3], v34, s9, v[36:37]
	v_readlane_b32 s12, v251, 26
	v_readlane_b32 s13, v251, 27
	v_readlane_b32 s14, v251, 28
	s_waitcnt vmcnt(6)
	ds_write_b128 v8, v[0:3]
	s_waitcnt vmcnt(5)
	ds_write_b128 v32, v[4:7]
	s_waitcnt vmcnt(4)
	ds_write_b128 v34, v[12:15] offset:18432
	v_mad_u64_u32 v[0:1], s[2:3], v38, s9, v[36:37]
	s_waitcnt vmcnt(3)
	ds_write_b128 v0, v[16:19] offset:18432
	v_mad_u64_u32 v[0:1], s[2:3], v40, s9, v[36:37]
	v_readlane_b32 s15, v251, 29
	v_readlane_b32 s16, v251, 30
	v_readlane_b32 s17, v251, 31
	s_waitcnt vmcnt(2)
	ds_write_b128 v0, v[20:23] offset:18432
	v_mad_u64_u32 v[0:1], s[2:3], v42, s9, v[36:37]
	s_waitcnt vmcnt(1)
	ds_write_b128 v0, v[24:27] offset:18432
	v_lshlrev_b32_e32 v0, 7, v44
	v_readlane_b32 s2, v254, 40
	v_bfe_u32 v22, v11, 7, 1
	v_readlane_b32 s18, v251, 32
	v_add3_u32 v0, s2, v0, v46
	v_readlane_b32 s19, v251, 33
	v_readlane_b32 s20, v251, 34
	v_readlane_b32 s21, v251, 35
	v_readlane_b32 s22, v251, 36
	v_readlane_b32 s23, v251, 37
	s_waitcnt vmcnt(0)
	ds_write_b128 v0, v[28:31]
	v_and_b32_e32 v13, 0x7f, v11
	v_lshlrev_b32_e32 v0, 11, v22
	v_readlane_b32 s24, v251, 38
	v_readlane_b32 s25, v251, 39
	v_readlane_b32 s26, v251, 40
	v_readlane_b32 s27, v251, 41
	s_mov_b64 s[12:13], s[16:17]
	v_or3_b32 v112, v0, s5, v13
	s_mov_b64 s[14:15], s[18:19]
	s_mov_b64 s[16:17], s[20:21]
	s_mov_b64 s[18:19], s[22:23]
	s_mov_b64 s[20:21], s[24:25]
	v_lshl_add_u64 v[2:3], v[112:113], 2, s[20:21]
	s_movk_i32 s2, 0x1000
	v_add_co_u32_e32 v20, vcc, s2, v2
	s_waitcnt lgkmcnt(0)
	s_nop 0
	v_addc_co_u32_e32 v21, vcc, 0, v3, vcc
	s_barrier
	v_lshlrev_b32_e32 v12, 7, v22
	s_mov_b64 s[22:23], s[26:27]
	v_or3_b32 v112, v12, s6, v13
	v_lshl_add_u64 v[114:115], v[112:113], 2, s[22:23]
	s_cmp_eq_u32 s97, 0
	s_cbranch_scc1 .Lgw_skip
	global_load_dword v204, v[2:3], off
	global_load_dword v205, v[2:3], off offset:512
	global_load_dword v206, v[2:3], off offset:1024
	global_load_dword v207, v[2:3], off offset:1536
	global_load_dword v208, v[2:3], off offset:2048
	global_load_dword v209, v[2:3], off offset:2560
	global_load_dword v210, v[2:3], off offset:3072
	global_load_dword v211, v[2:3], off offset:3584
	global_load_dword v212, v[20:21], off
	global_load_dword v213, v[20:21], off offset:512
	global_load_dword v214, v[20:21], off offset:1024
	global_load_dword v215, v[20:21], off offset:1536
	global_load_dword v216, v[20:21], off offset:2048
	global_load_dword v217, v[20:21], off offset:2560
	global_load_dword v218, v[20:21], off offset:3072
	global_load_dword v219, v[20:21], off offset:3584
	global_load_dword v220, v[114:115], off
	s_mov_b32 s97, 0
; DI float logsig(float x) { return fminf(x, 0.f) - __logf(1.f + __expf(-fabsf(x))); }
; DI void gla_prep_item(const KP& P, int layer, int b, int tb, LAS unsigned char* lds) {
;     ...
;       for (int i = 0; i < 32; ++i) { const int t = (tid >> 8) + 2 * i; float pre = bias;
; #pragma unroll
;           for (int k = 0; k < 16; ++k) pre += Gt[t * 32 + dir * 16 + k] * w[k];
;           Bc[(dir * 64 + t) * 128 + ch] = logsig(pre) * (1.f / 16.f); } }
.Lgw_skip:
	v_ashrrev_i32_e32 v41, 8, v11
	v_lshlrev_b32_e32 v21, 9, v41
	v_lshl_add_u32 v21, v22, 15, v21
	v_lshlrev_b32_e32 v23, 6, v22
	v_lshl_or_b32 v21, v13, 2, v21
	s_movk_i32 s68, 0x1800
	s_movk_i32 s30, 0x120
	v_lshlrev_b32_e32 v12, 2, v11
	v_add_u32_e32 v21, 0xd000, v21
	v_lshl_or_b32 v22, v41, 7, v23
	s_mov_b32 s2, 32
	s_mov_b32 s3, 0x800000
	s_mov_b32 s9, 0xbfb8aa3b
	s_mov_b32 s10, 0x3f317217
	s_mov_b32 s11, 0x7f800000
	s_waitcnt vmcnt(0)
.Lgate_loop:
	v_add_u32_e32 v136, 0x1d000, v22
	ds_read_b128 v[24:27], v136 offset:0
	ds_read_b128 v[28:31], v136 offset:16
	ds_read_b128 v[32:35], v136 offset:32
	ds_read_b128 v[36:39], v136 offset:48
	ds_read_b128 v[46:49], v136 offset:256
	ds_read_b128 v[50:53], v136 offset:272
	ds_read_b128 v[54:57], v136 offset:288
	ds_read_b128 v[58:61], v136 offset:304
	ds_read_b128 v[116:119], v136 offset:512
	ds_read_b128 v[120:123], v136 offset:528
	ds_read_b128 v[124:127], v136 offset:544
	ds_read_b128 v[128:131], v136 offset:560
	ds_read_b128 v[152:155], v136 offset:768
	ds_read_b128 v[156:159], v136 offset:784
	ds_read_b128 v[160:163], v136 offset:800
	ds_read_b128 v[164:167], v136 offset:816
	s_add_i32 s2, s2, -4
	v_add_u32_e32 v22, 0x400, v22
	s_waitcnt lgkmcnt(0)
	v_fma_f32 v42, v204, v24, v220
	v_fma_f32 v62, v204, v46, v220
	v_fma_f32 v132, v204, v116, v220
	v_fma_f32 v168, v204, v152, v220
	v_fmac_f32_e32 v42, v205, v25
	v_fmac_f32_e32 v62, v205, v47
	v_fmac_f32_e32 v132, v205, v117
	v_fmac_f32_e32 v168, v205, v153
	v_fmac_f32_e32 v42, v206, v26
	v_fmac_f32_e32 v62, v206, v48
	v_fmac_f32_e32 v132, v206, v118
	v_fmac_f32_e32 v168, v206, v154
	v_fmac_f32_e32 v42, v207, v27
	v_fmac_f32_e32 v62, v207, v49
	v_fmac_f32_e32 v132, v207, v119
	v_fmac_f32_e32 v168, v207, v155
	v_fmac_f32_e32 v42, v208, v28
	v_fmac_f32_e32 v62, v208, v50
	v_fmac_f32_e32 v132, v208, v120
	v_fmac_f32_e32 v168, v208, v156
	v_pk_mul_f32 v[30:31], v[210:211], v[30:31]
	v_pk_mul_f32 v[52:53], v[210:211], v[52:53]
	v_pk_mul_f32 v[122:123], v[210:211], v[122:123]
	v_pk_mul_f32 v[158:159], v[210:211], v[158:159]
	v_fmac_f32_e32 v42, v209, v29
	v_fmac_f32_e32 v62, v209, v51
	v_fmac_f32_e32 v132, v209, v121
	v_fmac_f32_e32 v168, v209, v157
	v_add_f32_e32 v42, v42, v30
	v_add_f32_e32 v62, v62, v52
	v_add_f32_e32 v132, v132, v122
	v_add_f32_e32 v168, v168, v158
	v_pk_mul_f32 v[32:33], v[212:213], v[32:33]
	v_pk_mul_f32 v[54:55], v[212:213], v[54:55]
	v_pk_mul_f32 v[124:125], v[212:213], v[124:125]
	v_pk_mul_f32 v[160:161], v[212:213], v[160:161]
	v_add_f32_e32 v42, v42, v31
	v_add_f32_e32 v62, v62, v53
	v_add_f32_e32 v132, v132, v123
	v_add_f32_e32 v168, v168, v159
	v_add_f32_e32 v42, v42, v32
	v_add_f32_e32 v62, v62, v54
	v_add_f32_e32 v132, v132, v124
	v_add_f32_e32 v168, v168, v160
	v_pk_mul_f32 v[34:35], v[214:215], v[34:35]
	v_pk_mul_f32 v[56:57], v[214:215], v[56:57]
	v_pk_mul_f32 v[126:127], v[214:215], v[126:127]
	v_pk_mul_f32 v[162:163], v[214:215], v[162:163]
	v_add_f32_e32 v42, v42, v33
	v_add_f32_e32 v62, v62, v55
	v_add_f32_e32 v132, v132, v125
	v_add_f32_e32 v168, v168, v161
	v_add_f32_e32 v42, v42, v34
	v_add_f32_e32 v62, v62, v56
	v_add_f32_e32 v132, v132, v126
	v_add_f32_e32 v168, v168, v162
	v_pk_mul_f32 v[36:37], v[216:217], v[36:37]
	v_pk_mul_f32 v[58:59], v[216:217], v[58:59]
	v_pk_mul_f32 v[128:129], v[216:217], v[128:129]
	v_pk_mul_f32 v[164:165], v[216:217], v[164:165]
	v_add_f32_e32 v42, v42, v35
	v_add_f32_e32 v62, v62, v57
	v_add_f32_e32 v132, v132, v127
	v_add_f32_e32 v168, v168, v163
	v_add_f32_e32 v42, v42, v36
	v_add_f32_e32 v62, v62, v58
	v_add_f32_e32 v132, v132, v128
	v_add_f32_e32 v168, v168, v164
	v_pk_mul_f32 v[38:39], v[218:219], v[38:39]
	v_pk_mul_f32 v[60:61], v[218:219], v[60:61]
	v_pk_mul_f32 v[130:131], v[218:219], v[130:131]
	v_pk_mul_f32 v[166:167], v[218:219], v[166:167]
	v_add_f32_e32 v42, v42, v37
	v_add_f32_e32 v62, v62, v59
	v_add_f32_e32 v132, v132, v129
	v_add_f32_e32 v168, v168, v165
	v_add_f32_e32 v42, v42, v38
	v_add_f32_e32 v62, v62, v60
	v_add_f32_e32 v132, v132, v130
	v_add_f32_e32 v168, v168, v166
	v_add_f32_e32 v42, v42, v39
	v_add_f32_e32 v62, v62, v61
	v_add_f32_e32 v132, v132, v131
	v_add_f32_e32 v168, v168, v167
	v_min_f32_e32 v43, 0, v42
	v_min_f32_e32 v63, 0, v62
	v_min_f32_e32 v133, 0, v132
	v_min_f32_e32 v169, 0, v168
	v_mul_f32_e64 v24, |v42|, s9
	v_mul_f32_e64 v46, |v62|, s9
	v_mul_f32_e64 v116, |v132|, s9
	v_mul_f32_e64 v152, |v168|, s9
	v_exp_f32_e32 v24, v24
	v_exp_f32_e32 v46, v46
	v_exp_f32_e32 v116, v116
	v_exp_f32_e32 v152, v152
	v_add_f32_e32 v24, 1.0, v24
	v_add_f32_e32 v46, 1.0, v46
	v_add_f32_e32 v116, 1.0, v116
	v_add_f32_e32 v152, 1.0, v152
	v_cmp_gt_f32_e64 s[74:75], s3, v24
	v_cmp_gt_f32_e64 s[76:77], s3, v46
	v_cmp_gt_f32_e64 s[78:79], s3, v116
	v_cmp_gt_f32_e64 s[80:81], s3, v152
	v_cndmask_b32_e64 v44, 0, 32, s[74:75]
	v_cndmask_b32_e64 v64, 0, 32, s[76:77]
	v_cndmask_b32_e64 v134, 0, 32, s[78:79]
	v_cndmask_b32_e64 v170, 0, 32, s[80:81]
	v_ldexp_f32 v24, v24, v44
	v_ldexp_f32 v46, v46, v64
	v_ldexp_f32 v116, v116, v134
	v_ldexp_f32 v152, v152, v170
	v_log_f32_e32 v24, v24
	v_log_f32_e32 v46, v46
	v_log_f32_e32 v116, v116
	v_log_f32_e32 v152, v152
	v_cndmask_b32_e64 v44, 0, v148, s[74:75]
	v_cndmask_b32_e64 v64, 0, v148, s[76:77]
	v_cndmask_b32_e64 v134, 0, v148, s[78:79]
	v_cndmask_b32_e64 v170, 0, v148, s[80:81]
	v_mul_f32_e32 v45, 0x3f317217, v24
	v_mul_f32_e32 v114, 0x3f317217, v46
	v_mul_f32_e32 v135, 0x3f317217, v116
	v_mul_f32_e32 v171, 0x3f317217, v152
	v_fma_f32 v45, v24, s10, -v45
	v_fma_f32 v114, v46, s10, -v114
	v_fma_f32 v135, v116, s10, -v135
	v_fma_f32 v171, v152, s10, -v171
	v_fmac_f32_e32 v45, 0x3377d1cf, v24
	v_fmac_f32_e32 v114, 0x3377d1cf, v46
	v_fmac_f32_e32 v135, 0x3377d1cf, v116
	v_fmac_f32_e32 v171, 0x3377d1cf, v152
	v_fmac_f32_e32 v45, 0x3f317217, v24
	v_fmac_f32_e32 v114, 0x3f317217, v46
	v_fmac_f32_e32 v135, 0x3f317217, v116
	v_fmac_f32_e32 v171, 0x3f317217, v152
	v_cmp_lt_f32_e64 s[74:75], |v24|, s11
	v_cmp_lt_f32_e64 s[76:77], |v46|, s11
	v_cmp_lt_f32_e64 s[78:79], |v116|, s11
	v_cmp_lt_f32_e64 s[80:81], |v152|, s11
	v_cndmask_b32_e64 v24, v24, v45, s[74:75]
	v_cndmask_b32_e64 v46, v46, v114, s[76:77]
	v_cndmask_b32_e64 v116, v116, v135, s[78:79]
	v_cndmask_b32_e64 v152, v152, v171, s[80:81]
	v_sub_f32_e32 v24, v24, v44
	v_sub_f32_e32 v46, v46, v64
	v_sub_f32_e32 v116, v116, v134
	v_sub_f32_e32 v152, v152, v170
	v_sub_f32_e32 v24, v43, v24
	v_sub_f32_e32 v46, v63, v46
	v_sub_f32_e32 v116, v133, v116
	v_sub_f32_e32 v152, v169, v152
	v_mul_f32_e32 v24, 0x3d800000, v24
	v_mul_f32_e32 v46, 0x3d800000, v46
	v_mul_f32_e32 v116, 0x3d800000, v116
	v_mul_f32_e32 v152, 0x3d800000, v152
	ds_write_b32 v21, v24
	ds_write_b32 v21, v46 offset:1024
	ds_write_b32 v21, v116 offset:2048
	ds_write_b32 v21, v152 offset:3072
	v_add_u32_e32 v21, 0x1000, v21
	s_cmp_eq_u32 s2, 0
	s_cbranch_scc0 .Lgate_loop
; DI void gla_prep_item(const KP& P, int layer, int b, int tb, LAS unsigned char* lds) {
;     ...
;     if (tid < 256) { const int dir = tid >> 7, ch = tid & 127; float run = 0.f;
;         for (int step = 0; step < 64; ++step) { const int t = dir ? 63 - step : step;
;             run += Bc[(dir * 64 + t) * 128 + ch]; Bc[(dir * 64 + t) * 128 + ch] = run; BG[(R0 + t) * 256 + dir * 128 + ch] = run; } }
	s_movk_i32 s2, 0x100
	v_cmp_gt_i32_e32 vcc, s2, v11
	s_waitcnt lgkmcnt(0)
	s_barrier
	s_and_saveexec_b64 s[2:3], vcc
	s_cbranch_execz .LBB0_286
	s_movk_i32 s9, 0x80
	v_lshlrev_b32_e32 v0, 8, v11
	v_cmp_gt_u32_e32 vcc, s9, v11
	v_and_b32_e32 v0, 0xffff8000, v0
	v_lshlrev_b32_e32 v112, 2, v13
	v_add3_u32 v4, 0, v0, v112
	v_cndmask_b32_e64 v2, 63, 0, vcc
	v_lshl_add_u32 v3, v2, 9, v4
	v_mov_b32_e32 v6, 0x200
	v_mov_b32_e32 v7, 0xfffffe00
	v_mov_b32_e32 v14, 0x400
	v_mov_b32_e32 v15, 0xfffffc00
	v_cndmask_b32_e32 v8, v7, v6, vcc
	v_cndmask_b32_e32 v14, v15, v14, vcc
	v_mov_b32_e32 v9, v3
	v_and_b32_e32 v0, 0xffffff80, v11
	v_readlane_b32 s10, v254, 14
	v_ashrrev_i32_e32 v1, 31, v0
	v_readlane_b32 s11, v254, 15
	v_ashrrev_i32_e32 v15, 31, v14
	v_or_b32_e32 v6, s0, v2
	v_mov_b32_e32 v7, s1
	v_lshl_add_u64 v[0:1], v[0:1], 2, s[10:11]
	v_lshl_add_u64 v[0:1], v[0:1], 0, v[112:113]
	v_lshlrev_b64 v[6:7], 10, v[6:7]
	v_lshl_add_u64 v[6:7], v[0:1], 0, v[6:7]
	v_mov_b32_e32 v5, 0
	ds_read_b32 v20, v3 offset:53248
	v_add_u32_e32 v3, v8, v3
	ds_read_b32 v21, v3 offset:53248
	v_add_u32_e32 v3, v8, v3
	ds_read_b32 v22, v3 offset:53248
	v_add_u32_e32 v3, v8, v3
	ds_read_b32 v23, v3 offset:53248
	v_add_u32_e32 v3, v8, v3
	ds_read_b32 v24, v3 offset:53248
	v_add_u32_e32 v3, v8, v3
	ds_read_b32 v25, v3 offset:53248
	v_add_u32_e32 v3, v8, v3
	ds_read_b32 v26, v3 offset:53248
	v_add_u32_e32 v3, v8, v3
	ds_read_b32 v27, v3 offset:53248
	v_add_u32_e32 v3, v8, v3
	ds_read_b32 v28, v3 offset:53248
	v_add_u32_e32 v3, v8, v3
	ds_read_b32 v29, v3 offset:53248
	v_add_u32_e32 v3, v8, v3
	ds_read_b32 v30, v3 offset:53248
	v_add_u32_e32 v3, v8, v3
	ds_read_b32 v31, v3 offset:53248
	v_add_u32_e32 v3, v8, v3
	ds_read_b32 v32, v3 offset:53248
	v_add_u32_e32 v3, v8, v3
	ds_read_b32 v33, v3 offset:53248
	v_add_u32_e32 v3, v8, v3
	ds_read_b32 v34, v3 offset:53248
	v_add_u32_e32 v3, v8, v3
	ds_read_b32 v35, v3 offset:53248
	v_add_u32_e32 v3, v8, v3
	s_waitcnt lgkmcnt(0)
	v_add_f32_e32 v5, v5, v20
	ds_write_b32 v9, v5 offset:53248
	global_store_dword v[6:7], v5, off
	v_add_u32_e32 v9, v8, v9
	v_lshl_add_u64 v[6:7], v[6:7], 0, v[14:15]
	v_add_f32_e32 v5, v5, v21
	ds_write_b32 v9, v5 offset:53248
	global_store_dword v[6:7], v5, off
	v_add_u32_e32 v9, v8, v9
	v_lshl_add_u64 v[6:7], v[6:7], 0, v[14:15]
	v_add_f32_e32 v5, v5, v22
	ds_write_b32 v9, v5 offset:53248
	global_store_dword v[6:7], v5, off
	v_add_u32_e32 v9, v8, v9
	v_lshl_add_u64 v[6:7], v[6:7], 0, v[14:15]
	v_add_f32_e32 v5, v5, v23
	ds_write_b32 v9, v5 offset:53248
	global_store_dword v[6:7], v5, off
	v_add_u32_e32 v9, v8, v9
	v_lshl_add_u64 v[6:7], v[6:7], 0, v[14:15]
	v_add_f32_e32 v5, v5, v24
	ds_write_b32 v9, v5 offset:53248
	global_store_dword v[6:7], v5, off
	v_add_u32_e32 v9, v8, v9
	v_lshl_add_u64 v[6:7], v[6:7], 0, v[14:15]
	v_add_f32_e32 v5, v5, v25
	ds_write_b32 v9, v5 offset:53248
	global_store_dword v[6:7], v5, off
	v_add_u32_e32 v9, v8, v9
	v_lshl_add_u64 v[6:7], v[6:7], 0, v[14:15]
	v_add_f32_e32 v5, v5, v26
	ds_write_b32 v9, v5 offset:53248
	global_store_dword v[6:7], v5, off
	v_add_u32_e32 v9, v8, v9
	v_lshl_add_u64 v[6:7], v[6:7], 0, v[14:15]
	v_add_f32_e32 v5, v5, v27
	ds_write_b32 v9, v5 offset:53248
	global_store_dword v[6:7], v5, off
	v_add_u32_e32 v9, v8, v9
	v_lshl_add_u64 v[6:7], v[6:7], 0, v[14:15]
	v_add_f32_e32 v5, v5, v28
	ds_write_b32 v9, v5 offset:53248
	global_store_dword v[6:7], v5, off
	v_add_u32_e32 v9, v8, v9
	v_lshl_add_u64 v[6:7], v[6:7], 0, v[14:15]
	v_add_f32_e32 v5, v5, v29
	ds_write_b32 v9, v5 offset:53248
	global_store_dword v[6:7], v5, off
	v_add_u32_e32 v9, v8, v9
	v_lshl_add_u64 v[6:7], v[6:7], 0, v[14:15]
	v_add_f32_e32 v5, v5, v30
	ds_write_b32 v9, v5 offset:53248
	global_store_dword v[6:7], v5, off
	v_add_u32_e32 v9, v8, v9
	v_lshl_add_u64 v[6:7], v[6:7], 0, v[14:15]
	v_add_f32_e32 v5, v5, v31
	ds_write_b32 v9, v5 offset:53248
	global_store_dword v[6:7], v5, off
	v_add_u32_e32 v9, v8, v9
	v_lshl_add_u64 v[6:7], v[6:7], 0, v[14:15]
	v_add_f32_e32 v5, v5, v32
	ds_write_b32 v9, v5 offset:53248
	global_store_dword v[6:7], v5, off
	v_add_u32_e32 v9, v8, v9
	v_lshl_add_u64 v[6:7], v[6:7], 0, v[14:15]
	v_add_f32_e32 v5, v5, v33
	ds_write_b32 v9, v5 offset:53248
	global_store_dword v[6:7], v5, off
	v_add_u32_e32 v9, v8, v9
	v_lshl_add_u64 v[6:7], v[6:7], 0, v[14:15]
	v_add_f32_e32 v5, v5, v34
	ds_write_b32 v9, v5 offset:53248
	global_store_dword v[6:7], v5, off
	v_add_u32_e32 v9, v8, v9
	v_lshl_add_u64 v[6:7], v[6:7], 0, v[14:15]
	v_add_f32_e32 v5, v5, v35
	ds_write_b32 v9, v5 offset:53248
	global_store_dword v[6:7], v5, off
	v_add_u32_e32 v9, v8, v9
	v_lshl_add_u64 v[6:7], v[6:7], 0, v[14:15]
	ds_read_b32 v20, v3 offset:53248
	v_add_u32_e32 v3, v8, v3
	ds_read_b32 v21, v3 offset:53248
	v_add_u32_e32 v3, v8, v3
	ds_read_b32 v22, v3 offset:53248
	v_add_u32_e32 v3, v8, v3
	ds_read_b32 v23, v3 offset:53248
	v_add_u32_e32 v3, v8, v3
	ds_read_b32 v24, v3 offset:53248
	v_add_u32_e32 v3, v8, v3
	ds_read_b32 v25, v3 offset:53248
	v_add_u32_e32 v3, v8, v3
	ds_read_b32 v26, v3 offset:53248
	v_add_u32_e32 v3, v8, v3
	ds_read_b32 v27, v3 offset:53248
	v_add_u32_e32 v3, v8, v3
	ds_read_b32 v28, v3 offset:53248
	v_add_u32_e32 v3, v8, v3
	ds_read_b32 v29, v3 offset:53248
	v_add_u32_e32 v3, v8, v3
	ds_read_b32 v30, v3 offset:53248
	v_add_u32_e32 v3, v8, v3
	ds_read_b32 v31, v3 offset:53248
	v_add_u32_e32 v3, v8, v3
	ds_read_b32 v32, v3 offset:53248
	v_add_u32_e32 v3, v8, v3
	ds_read_b32 v33, v3 offset:53248
	v_add_u32_e32 v3, v8, v3
	ds_read_b32 v34, v3 offset:53248
	v_add_u32_e32 v3, v8, v3
	ds_read_b32 v35, v3 offset:53248
	v_add_u32_e32 v3, v8, v3
	s_waitcnt lgkmcnt(0)
; DI void gla_prep_item(const KP& P, int layer, int b, int tb, LAS unsigned char* lds) {
;     ...
;     if (tid < 256) { const int dir = tid >> 7, ch = tid & 127; float run = 0.f;
;         for (int step = 0; step < 64; ++step) { const int t = dir ? 63 - step : step;
;             run += Bc[(dir * 64 + t) * 128 + ch]; Bc[(dir * 64 + t) * 128 + ch] = run; BG[(R0 + t) * 256 + dir * 128 + ch] = run; } }
	v_add_f32_e32 v5, v5, v20
	ds_write_b32 v9, v5 offset:53248
	global_store_dword v[6:7], v5, off
	v_add_u32_e32 v9, v8, v9
	v_lshl_add_u64 v[6:7], v[6:7], 0, v[14:15]
	v_add_f32_e32 v5, v5, v21
	ds_write_b32 v9, v5 offset:53248
	global_store_dword v[6:7], v5, off
	v_add_u32_e32 v9, v8, v9
	v_lshl_add_u64 v[6:7], v[6:7], 0, v[14:15]
	v_add_f32_e32 v5, v5, v22
	ds_write_b32 v9, v5 offset:53248
	global_store_dword v[6:7], v5, off
	v_add_u32_e32 v9, v8, v9
	v_lshl_add_u64 v[6:7], v[6:7], 0, v[14:15]
	v_add_f32_e32 v5, v5, v23
	ds_write_b32 v9, v5 offset:53248
	global_store_dword v[6:7], v5, off
	v_add_u32_e32 v9, v8, v9
	v_lshl_add_u64 v[6:7], v[6:7], 0, v[14:15]
	v_add_f32_e32 v5, v5, v24
	ds_write_b32 v9, v5 offset:53248
	global_store_dword v[6:7], v5, off
	v_add_u32_e32 v9, v8, v9
	v_lshl_add_u64 v[6:7], v[6:7], 0, v[14:15]
	v_add_f32_e32 v5, v5, v25
	ds_write_b32 v9, v5 offset:53248
	global_store_dword v[6:7], v5, off
	v_add_u32_e32 v9, v8, v9
	v_lshl_add_u64 v[6:7], v[6:7], 0, v[14:15]
	v_add_f32_e32 v5, v5, v26
	ds_write_b32 v9, v5 offset:53248
	global_store_dword v[6:7], v5, off
	v_add_u32_e32 v9, v8, v9
	v_lshl_add_u64 v[6:7], v[6:7], 0, v[14:15]
	v_add_f32_e32 v5, v5, v27
	ds_write_b32 v9, v5 offset:53248
	global_store_dword v[6:7], v5, off
	v_add_u32_e32 v9, v8, v9
	v_lshl_add_u64 v[6:7], v[6:7], 0, v[14:15]
	v_add_f32_e32 v5, v5, v28
	ds_write_b32 v9, v5 offset:53248
	global_store_dword v[6:7], v5, off
	v_add_u32_e32 v9, v8, v9
	v_lshl_add_u64 v[6:7], v[6:7], 0, v[14:15]
	v_add_f32_e32 v5, v5, v29
	ds_write_b32 v9, v5 offset:53248
	global_store_dword v[6:7], v5, off
	v_add_u32_e32 v9, v8, v9
	v_lshl_add_u64 v[6:7], v[6:7], 0, v[14:15]
	v_add_f32_e32 v5, v5, v30
	ds_write_b32 v9, v5 offset:53248
	global_store_dword v[6:7], v5, off
	v_add_u32_e32 v9, v8, v9
	v_lshl_add_u64 v[6:7], v[6:7], 0, v[14:15]
	v_add_f32_e32 v5, v5, v31
	ds_write_b32 v9, v5 offset:53248
	global_store_dword v[6:7], v5, off
	v_add_u32_e32 v9, v8, v9
	v_lshl_add_u64 v[6:7], v[6:7], 0, v[14:15]
	v_add_f32_e32 v5, v5, v32
	ds_write_b32 v9, v5 offset:53248
	global_store_dword v[6:7], v5, off
	v_add_u32_e32 v9, v8, v9
	v_lshl_add_u64 v[6:7], v[6:7], 0, v[14:15]
	v_add_f32_e32 v5, v5, v33
	ds_write_b32 v9, v5 offset:53248
	global_store_dword v[6:7], v5, off
	v_add_u32_e32 v9, v8, v9
	v_lshl_add_u64 v[6:7], v[6:7], 0, v[14:15]
	v_add_f32_e32 v5, v5, v34
	ds_write_b32 v9, v5 offset:53248
	global_store_dword v[6:7], v5, off
	v_add_u32_e32 v9, v8, v9
	v_lshl_add_u64 v[6:7], v[6:7], 0, v[14:15]
	v_add_f32_e32 v5, v5, v35
	ds_write_b32 v9, v5 offset:53248
	global_store_dword v[6:7], v5, off
	v_add_u32_e32 v9, v8, v9
	v_lshl_add_u64 v[6:7], v[6:7], 0, v[14:15]
	ds_read_b32 v20, v3 offset:53248
	v_add_u32_e32 v3, v8, v3
	ds_read_b32 v21, v3 offset:53248
	v_add_u32_e32 v3, v8, v3
	ds_read_b32 v22, v3 offset:53248
	v_add_u32_e32 v3, v8, v3
	ds_read_b32 v23, v3 offset:53248
	v_add_u32_e32 v3, v8, v3
	ds_read_b32 v24, v3 offset:53248
	v_add_u32_e32 v3, v8, v3
	ds_read_b32 v25, v3 offset:53248
	v_add_u32_e32 v3, v8, v3
	ds_read_b32 v26, v3 offset:53248
	v_add_u32_e32 v3, v8, v3
	ds_read_b32 v27, v3 offset:53248
	v_add_u32_e32 v3, v8, v3
	ds_read_b32 v28, v3 offset:53248
	v_add_u32_e32 v3, v8, v3
	ds_read_b32 v29, v3 offset:53248
	v_add_u32_e32 v3, v8, v3
	ds_read_b32 v30, v3 offset:53248
	v_add_u32_e32 v3, v8, v3
	ds_read_b32 v31, v3 offset:53248
	v_add_u32_e32 v3, v8, v3
	ds_read_b32 v32, v3 offset:53248
	v_add_u32_e32 v3, v8, v3
	ds_read_b32 v33, v3 offset:53248
	v_add_u32_e32 v3, v8, v3
	ds_read_b32 v34, v3 offset:53248
	v_add_u32_e32 v3, v8, v3
	ds_read_b32 v35, v3 offset:53248
	v_add_u32_e32 v3, v8, v3
	s_waitcnt lgkmcnt(0)
; DI void gla_prep_item(const KP& P, int layer, int b, int tb, LAS unsigned char* lds) {
;     ...
;     if (tid < 256) { const int dir = tid >> 7, ch = tid & 127; float run = 0.f;
;         for (int step = 0; step < 64; ++step) { const int t = dir ? 63 - step : step;
;             run += Bc[(dir * 64 + t) * 128 + ch]; Bc[(dir * 64 + t) * 128 + ch] = run; BG[(R0 + t) * 256 + dir * 128 + ch] = run; } }
	v_add_f32_e32 v5, v5, v20
	ds_write_b32 v9, v5 offset:53248
	global_store_dword v[6:7], v5, off
	v_add_u32_e32 v9, v8, v9
	v_lshl_add_u64 v[6:7], v[6:7], 0, v[14:15]
	v_add_f32_e32 v5, v5, v21
	ds_write_b32 v9, v5 offset:53248
	global_store_dword v[6:7], v5, off
	v_add_u32_e32 v9, v8, v9
	v_lshl_add_u64 v[6:7], v[6:7], 0, v[14:15]
	v_add_f32_e32 v5, v5, v22
	ds_write_b32 v9, v5 offset:53248
	global_store_dword v[6:7], v5, off
	v_add_u32_e32 v9, v8, v9
	v_lshl_add_u64 v[6:7], v[6:7], 0, v[14:15]
	v_add_f32_e32 v5, v5, v23
	ds_write_b32 v9, v5 offset:53248
	global_store_dword v[6:7], v5, off
	v_add_u32_e32 v9, v8, v9
	v_lshl_add_u64 v[6:7], v[6:7], 0, v[14:15]
	v_add_f32_e32 v5, v5, v24
	ds_write_b32 v9, v5 offset:53248
	global_store_dword v[6:7], v5, off
	v_add_u32_e32 v9, v8, v9
	v_lshl_add_u64 v[6:7], v[6:7], 0, v[14:15]
	v_add_f32_e32 v5, v5, v25
	ds_write_b32 v9, v5 offset:53248
	global_store_dword v[6:7], v5, off
	v_add_u32_e32 v9, v8, v9
	v_lshl_add_u64 v[6:7], v[6:7], 0, v[14:15]
	v_add_f32_e32 v5, v5, v26
	ds_write_b32 v9, v5 offset:53248
	global_store_dword v[6:7], v5, off
	v_add_u32_e32 v9, v8, v9
	v_lshl_add_u64 v[6:7], v[6:7], 0, v[14:15]
	v_add_f32_e32 v5, v5, v27
	ds_write_b32 v9, v5 offset:53248
	global_store_dword v[6:7], v5, off
	v_add_u32_e32 v9, v8, v9
	v_lshl_add_u64 v[6:7], v[6:7], 0, v[14:15]
	v_add_f32_e32 v5, v5, v28
	ds_write_b32 v9, v5 offset:53248
	global_store_dword v[6:7], v5, off
	v_add_u32_e32 v9, v8, v9
	v_lshl_add_u64 v[6:7], v[6:7], 0, v[14:15]
	v_add_f32_e32 v5, v5, v29
	ds_write_b32 v9, v5 offset:53248
	global_store_dword v[6:7], v5, off
	v_add_u32_e32 v9, v8, v9
	v_lshl_add_u64 v[6:7], v[6:7], 0, v[14:15]
	v_add_f32_e32 v5, v5, v30
	ds_write_b32 v9, v5 offset:53248
	global_store_dword v[6:7], v5, off
	v_add_u32_e32 v9, v8, v9
	v_lshl_add_u64 v[6:7], v[6:7], 0, v[14:15]
	v_add_f32_e32 v5, v5, v31
	ds_write_b32 v9, v5 offset:53248
	global_store_dword v[6:7], v5, off
	v_add_u32_e32 v9, v8, v9
	v_lshl_add_u64 v[6:7], v[6:7], 0, v[14:15]
	v_add_f32_e32 v5, v5, v32
	ds_write_b32 v9, v5 offset:53248
	global_store_dword v[6:7], v5, off
	v_add_u32_e32 v9, v8, v9
	v_lshl_add_u64 v[6:7], v[6:7], 0, v[14:15]
	v_add_f32_e32 v5, v5, v33
	ds_write_b32 v9, v5 offset:53248
	global_store_dword v[6:7], v5, off
	v_add_u32_e32 v9, v8, v9
	v_lshl_add_u64 v[6:7], v[6:7], 0, v[14:15]
	v_add_f32_e32 v5, v5, v34
	ds_write_b32 v9, v5 offset:53248
	global_store_dword v[6:7], v5, off
	v_add_u32_e32 v9, v8, v9
	v_lshl_add_u64 v[6:7], v[6:7], 0, v[14:15]
	v_add_f32_e32 v5, v5, v35
	ds_write_b32 v9, v5 offset:53248
	global_store_dword v[6:7], v5, off
	v_add_u32_e32 v9, v8, v9
	v_lshl_add_u64 v[6:7], v[6:7], 0, v[14:15]
	ds_read_b32 v20, v3 offset:53248
	v_add_u32_e32 v3, v8, v3
	ds_read_b32 v21, v3 offset:53248
	v_add_u32_e32 v3, v8, v3
	ds_read_b32 v22, v3 offset:53248
	v_add_u32_e32 v3, v8, v3
	ds_read_b32 v23, v3 offset:53248
	v_add_u32_e32 v3, v8, v3
	ds_read_b32 v24, v3 offset:53248
	v_add_u32_e32 v3, v8, v3
	ds_read_b32 v25, v3 offset:53248
	v_add_u32_e32 v3, v8, v3
	ds_read_b32 v26, v3 offset:53248
	v_add_u32_e32 v3, v8, v3
	ds_read_b32 v27, v3 offset:53248
	v_add_u32_e32 v3, v8, v3
	ds_read_b32 v28, v3 offset:53248
	v_add_u32_e32 v3, v8, v3
	ds_read_b32 v29, v3 offset:53248
	v_add_u32_e32 v3, v8, v3
	ds_read_b32 v30, v3 offset:53248
	v_add_u32_e32 v3, v8, v3
	ds_read_b32 v31, v3 offset:53248
	v_add_u32_e32 v3, v8, v3
	ds_read_b32 v32, v3 offset:53248
	v_add_u32_e32 v3, v8, v3
	ds_read_b32 v33, v3 offset:53248
	v_add_u32_e32 v3, v8, v3
	ds_read_b32 v34, v3 offset:53248
	v_add_u32_e32 v3, v8, v3
	ds_read_b32 v35, v3 offset:53248
	v_add_u32_e32 v3, v8, v3
	s_waitcnt lgkmcnt(0)
	v_add_f32_e32 v5, v5, v20
	ds_write_b32 v9, v5 offset:53248
	global_store_dword v[6:7], v5, off
	v_add_u32_e32 v9, v8, v9
	v_lshl_add_u64 v[6:7], v[6:7], 0, v[14:15]
	v_add_f32_e32 v5, v5, v21
	ds_write_b32 v9, v5 offset:53248
	global_store_dword v[6:7], v5, off
	v_add_u32_e32 v9, v8, v9
	v_lshl_add_u64 v[6:7], v[6:7], 0, v[14:15]
	v_add_f32_e32 v5, v5, v22
	ds_write_b32 v9, v5 offset:53248
	global_store_dword v[6:7], v5, off
	v_add_u32_e32 v9, v8, v9
	v_lshl_add_u64 v[6:7], v[6:7], 0, v[14:15]
	v_add_f32_e32 v5, v5, v23
	ds_write_b32 v9, v5 offset:53248
	global_store_dword v[6:7], v5, off
	v_add_u32_e32 v9, v8, v9
	v_lshl_add_u64 v[6:7], v[6:7], 0, v[14:15]
	v_add_f32_e32 v5, v5, v24
	ds_write_b32 v9, v5 offset:53248
	global_store_dword v[6:7], v5, off
	v_add_u32_e32 v9, v8, v9
	v_lshl_add_u64 v[6:7], v[6:7], 0, v[14:15]
	v_add_f32_e32 v5, v5, v25
	ds_write_b32 v9, v5 offset:53248
	global_store_dword v[6:7], v5, off
	v_add_u32_e32 v9, v8, v9
	v_lshl_add_u64 v[6:7], v[6:7], 0, v[14:15]
	v_add_f32_e32 v5, v5, v26
	ds_write_b32 v9, v5 offset:53248
	global_store_dword v[6:7], v5, off
	v_add_u32_e32 v9, v8, v9
	v_lshl_add_u64 v[6:7], v[6:7], 0, v[14:15]
	v_add_f32_e32 v5, v5, v27
	ds_write_b32 v9, v5 offset:53248
	global_store_dword v[6:7], v5, off
	v_add_u32_e32 v9, v8, v9
	v_lshl_add_u64 v[6:7], v[6:7], 0, v[14:15]
	v_add_f32_e32 v5, v5, v28
	ds_write_b32 v9, v5 offset:53248
	global_store_dword v[6:7], v5, off
	v_add_u32_e32 v9, v8, v9
	v_lshl_add_u64 v[6:7], v[6:7], 0, v[14:15]
	v_add_f32_e32 v5, v5, v29
	ds_write_b32 v9, v5 offset:53248
	global_store_dword v[6:7], v5, off
	v_add_u32_e32 v9, v8, v9
	v_lshl_add_u64 v[6:7], v[6:7], 0, v[14:15]
	v_add_f32_e32 v5, v5, v30
	ds_write_b32 v9, v5 offset:53248
	global_store_dword v[6:7], v5, off
	v_add_u32_e32 v9, v8, v9
	v_lshl_add_u64 v[6:7], v[6:7], 0, v[14:15]
	v_add_f32_e32 v5, v5, v31
	ds_write_b32 v9, v5 offset:53248
	global_store_dword v[6:7], v5, off
	v_add_u32_e32 v9, v8, v9
	v_lshl_add_u64 v[6:7], v[6:7], 0, v[14:15]
	v_add_f32_e32 v5, v5, v32
	ds_write_b32 v9, v5 offset:53248
	global_store_dword v[6:7], v5, off
	v_add_u32_e32 v9, v8, v9
	v_lshl_add_u64 v[6:7], v[6:7], 0, v[14:15]
	v_add_f32_e32 v5, v5, v33
	ds_write_b32 v9, v5 offset:53248
	global_store_dword v[6:7], v5, off
	v_add_u32_e32 v9, v8, v9
	v_lshl_add_u64 v[6:7], v[6:7], 0, v[14:15]
	v_add_f32_e32 v5, v5, v34
	ds_write_b32 v9, v5 offset:53248
	global_store_dword v[6:7], v5, off
	v_add_u32_e32 v9, v8, v9
	v_lshl_add_u64 v[6:7], v[6:7], 0, v[14:15]
	v_add_f32_e32 v5, v5, v35
	ds_write_b32 v9, v5 offset:53248
	global_store_dword v[6:7], v5, off
	v_add_u32_e32 v9, v8, v9
	v_lshl_add_u64 v[6:7], v[6:7], 0, v[14:15]
